# GEMM2 and FF2: first K-loop iteration peeled with srcC=0, 64-bit zero moves of the accumulators dropped
# speedup vs baseline: 1.0027x; 1.0027x over previous
.LBB0_447:
	s_ashr_i32 s21, s20, 31
	v_cmp_lt_i64_e32 vcc, s[22:23], v[200:201]
	s_lshl_b64 s[22:23], s[20:21], 21
	s_add_u32 s22, s14, s22
	s_addc_u32 s23, s15, s23
	s_and_b64 s[26:27], vcc, exec
	s_cselect_b32 s21, s23, s39
	s_cselect_b32 s81, s22, s38
	s_ashr_i32 s19, s18, 31
	s_lshl_b64 s[26:27], s[18:19], 20
	s_add_u32 s26, s17, s26
	s_addc_u32 s27, s33, s27
	s_and_b64 s[42:43], vcc, exec
	s_cselect_b32 s19, s27, s47
	s_cselect_b32 s83, s26, s46
	s_ashr_i32 s29, s28, 31
	s_lshl_b64 s[42:43], s[28:29], 21
	s_add_u32 s84, s14, s42
	s_addc_u32 s85, s15, s43
	s_ashr_i32 s41, s40, 31
	s_lshl_b64 s[42:43], s[40:41], 16
	s_add_u32 s41, s84, s42
	s_addc_u32 s44, s85, s43
	s_add_u32 s41, s41, s8
	s_addc_u32 s45, s44, s9
	s_add_u32 s44, s41, 0x100000
	s_addc_u32 s45, s45, 0
	v_mov_b32_e32 v2, v0
	v_mov_b32_e32 v3, v0
	s_add_u32 s41, s46, 0x100
	v_mov_b32_e32 v1, v0
	s_addc_u32 s86, s47, 0
	v_lshl_add_u64 v[204:205], s[38:39], 0, v[196:197]
	v_lshl_add_u64 v[206:207], s[38:39], 0, v[198:199]
	s_mov_b32 s87, -2
	s_mov_b64 s[46:47], 0
	v_add_u32_e32 v1, s78, v210
	ds_read_b128 v[132:135], v1
	ds_read_b128 v[136:139], v1 offset:1024
	ds_read_b128 v[140:143], v1 offset:2048
	ds_read_b128 v[144:147], v1 offset:3072
	v_add_u32_e32 v1, s79, v210
	s_add_u32 s48, s38, s46
	ds_read_b128 v[148:151], v1
	ds_read_b128 v[152:155], v1 offset:1024
	ds_read_b128 v[156:159], v1 offset:2048
	ds_read_b128 v[160:163], v1 offset:3072
	s_addc_u32 s49, s39, s47
	s_add_u32 s48, s48, 0x10000
	s_addc_u32 s49, s49, 0
	s_cmp_eq_u32 s46, 0xf0000
	s_cselect_b32 s64, s81, s48
	s_cselect_b32 s65, s21, s49
	s_cselect_b32 s50, s83, s41
	s_cselect_b32 s51, s19, s86
	s_add_u32 s48, s64, 0x8000
	s_addc_u32 s49, s65, 0
	v_lshl_add_u64 v[2:3], v[204:205], 0, s[46:47]
	s_add_i32 m0, s35, 0xc000
	ds_read_b128 v[164:167], v211
	ds_read_b128 v[168:171], v211 offset:1024
	ds_read_b128 v[172:175], v211 offset:2048
	ds_read_b128 v[176:179], v211 offset:3072
	ds_read_b128 v[180:183], v211 offset:4096
	ds_read_b128 v[184:187], v211 offset:5120
	ds_read_b128 v[212:215], v211 offset:6144
	ds_read_b128 v[216:219], v211 offset:7168
	global_load_lds_dwordx4 v[2:3], off
	v_lshl_add_u64 v[2:3], v[206:207], 0, s[46:47]
	s_add_i32 m0, s35, 0xe000
	s_nop 0
	global_load_lds_dwordx4 v[2:3], off
	s_waitcnt vmcnt(8)
	s_waitcnt lgkmcnt(0)
	s_setprio 1
	s_barrier
	v_mfma_f32_16x16x32_bf16 v[128:131], v[132:135], v[164:167], 0
	v_mfma_f32_16x16x32_bf16 v[124:127], v[140:143], v[164:167], 0
	v_mfma_f32_16x16x32_bf16 v[112:115], v[132:135], v[172:175], 0
	v_mfma_f32_16x16x32_bf16 v[108:111], v[140:143], v[172:175], 0
	v_mfma_f32_16x16x32_bf16 v[96:99], v[132:135], v[180:183], 0
	v_mfma_f32_16x16x32_bf16 v[92:95], v[140:143], v[180:183], 0
	v_mfma_f32_16x16x32_bf16 v[80:83], v[132:135], v[212:215], 0
	v_mfma_f32_16x16x32_bf16 v[76:79], v[140:143], v[212:215], 0
	v_mfma_f32_16x16x32_bf16 v[128:131], v[136:139], v[168:171], v[128:131]
	v_mfma_f32_16x16x32_bf16 v[124:127], v[144:147], v[168:171], v[124:127]
	v_mfma_f32_16x16x32_bf16 v[112:115], v[136:139], v[176:179], v[112:115]
	v_mfma_f32_16x16x32_bf16 v[108:111], v[144:147], v[176:179], v[108:111]
	v_mfma_f32_16x16x32_bf16 v[96:99], v[136:139], v[184:187], v[96:99]
	v_mfma_f32_16x16x32_bf16 v[92:95], v[144:147], v[184:187], v[92:95]
	v_mfma_f32_16x16x32_bf16 v[80:83], v[136:139], v[216:219], v[80:83]
	v_mfma_f32_16x16x32_bf16 v[76:79], v[144:147], v[216:219], v[76:79]
	v_mfma_f32_16x16x32_bf16 v[120:123], v[148:151], v[164:167], 0
	v_mfma_f32_16x16x32_bf16 v[116:119], v[156:159], v[164:167], 0
	v_mfma_f32_16x16x32_bf16 v[104:107], v[148:151], v[172:175], 0
	v_mfma_f32_16x16x32_bf16 v[100:103], v[156:159], v[172:175], 0
	v_mfma_f32_16x16x32_bf16 v[88:91], v[148:151], v[180:183], 0
	v_mfma_f32_16x16x32_bf16 v[84:87], v[156:159], v[180:183], 0
	v_mfma_f32_16x16x32_bf16 v[72:75], v[148:151], v[212:215], 0
	v_mfma_f32_16x16x32_bf16 v[68:71], v[156:159], v[212:215], 0
	v_mfma_f32_16x16x32_bf16 v[120:123], v[152:155], v[168:171], v[120:123]
	v_mfma_f32_16x16x32_bf16 v[116:119], v[160:163], v[168:171], v[116:119]
	v_mfma_f32_16x16x32_bf16 v[104:107], v[152:155], v[176:179], v[104:107]
	v_mfma_f32_16x16x32_bf16 v[100:103], v[160:163], v[176:179], v[100:103]
	v_mfma_f32_16x16x32_bf16 v[88:91], v[152:155], v[184:187], v[88:91]
	v_mfma_f32_16x16x32_bf16 v[84:87], v[160:163], v[184:187], v[84:87]
	v_mfma_f32_16x16x32_bf16 v[72:75], v[152:155], v[216:219], v[72:75]
	v_mfma_f32_16x16x32_bf16 v[68:71], v[160:163], v[216:219], v[68:71]
	s_barrier
	s_setprio 0
	s_add_i32 s88, s78, s34
	s_mov_b32 m0, s88
	ds_read_b128 v[164:167], v211 offset:16384
	ds_read_b128 v[168:171], v211 offset:17408
	ds_read_b128 v[172:175], v211 offset:18432
	ds_read_b128 v[176:179], v211 offset:19456
	ds_read_b128 v[180:183], v211 offset:20480
	ds_read_b128 v[184:187], v211 offset:21504
	ds_read_b128 v[212:215], v211 offset:22528
	ds_read_b128 v[216:219], v211 offset:23552
	global_load_lds_dwordx4 v192, s[50:51]
	s_add_i32 m0, s88, 0x2000
	s_add_u32 s88, s50, 0x80000
	v_lshl_add_u64 v[222:223], s[50:51], 0, v[188:189]
	s_addc_u32 s89, s51, 0
	s_add_i32 s90, s79, s34
	global_load_lds_dwordx4 v[222:223], off
	s_mov_b32 m0, s90
	s_nop 0
	global_load_lds_dwordx4 v192, s[88:89]
	s_add_i32 m0, s90, 0x2000
	s_nop 0
	global_load_lds_dwordx4 v188, s[88:89]
	s_mov_b32 m0, s35
	s_nop 0
	global_load_lds_dwordx4 v194, s[64:65]
	s_mov_b32 m0, s56
	s_nop 0
	global_load_lds_dwordx4 v190, s[64:65]
	s_waitcnt vmcnt(8)
	s_waitcnt lgkmcnt(0)
	s_setprio 1
	s_barrier
	v_mfma_f32_16x16x32_bf16 v[64:67], v[132:135], v[164:167], 0
	v_mfma_f32_16x16x32_bf16 v[60:63], v[140:143], v[164:167], 0
	v_mfma_f32_16x16x32_bf16 v[48:51], v[132:135], v[172:175], 0
	v_mfma_f32_16x16x32_bf16 v[44:47], v[140:143], v[172:175], 0
	v_mfma_f32_16x16x32_bf16 v[32:35], v[132:135], v[180:183], 0
	v_mfma_f32_16x16x32_bf16 v[28:31], v[140:143], v[180:183], 0
	v_mfma_f32_16x16x32_bf16 v[16:19], v[132:135], v[212:215], 0
	v_mfma_f32_16x16x32_bf16 v[12:15], v[140:143], v[212:215], 0
	v_mfma_f32_16x16x32_bf16 v[64:67], v[136:139], v[168:171], v[64:67]
	v_mfma_f32_16x16x32_bf16 v[60:63], v[144:147], v[168:171], v[60:63]
	v_mfma_f32_16x16x32_bf16 v[48:51], v[136:139], v[176:179], v[48:51]
	v_mfma_f32_16x16x32_bf16 v[44:47], v[144:147], v[176:179], v[44:47]
	v_mfma_f32_16x16x32_bf16 v[32:35], v[136:139], v[184:187], v[32:35]
	v_mfma_f32_16x16x32_bf16 v[28:31], v[144:147], v[184:187], v[28:31]
	v_mfma_f32_16x16x32_bf16 v[16:19], v[136:139], v[216:219], v[16:19]
	v_mfma_f32_16x16x32_bf16 v[12:15], v[144:147], v[216:219], v[12:15]
	v_mfma_f32_16x16x32_bf16 v[56:59], v[148:151], v[164:167], 0
	v_mfma_f32_16x16x32_bf16 v[52:55], v[156:159], v[164:167], 0
	v_mfma_f32_16x16x32_bf16 v[40:43], v[148:151], v[172:175], 0
	v_mfma_f32_16x16x32_bf16 v[36:39], v[156:159], v[172:175], 0
	v_mfma_f32_16x16x32_bf16 v[24:27], v[148:151], v[180:183], 0
	v_mfma_f32_16x16x32_bf16 v[20:23], v[156:159], v[180:183], 0
	v_mfma_f32_16x16x32_bf16 v[8:11], v[148:151], v[212:215], 0
	v_mfma_f32_16x16x32_bf16 v[2:5], v[156:159], v[212:215], 0
	v_mfma_f32_16x16x32_bf16 v[56:59], v[152:155], v[168:171], v[56:59]
	v_mfma_f32_16x16x32_bf16 v[52:55], v[160:163], v[168:171], v[52:55]
	v_mfma_f32_16x16x32_bf16 v[40:43], v[152:155], v[176:179], v[40:43]
	v_mfma_f32_16x16x32_bf16 v[36:39], v[160:163], v[176:179], v[36:39]
	v_mfma_f32_16x16x32_bf16 v[24:27], v[152:155], v[184:187], v[24:27]
	v_mfma_f32_16x16x32_bf16 v[20:23], v[160:163], v[184:187], v[20:23]
	v_mfma_f32_16x16x32_bf16 v[8:11], v[152:155], v[216:219], v[8:11]
	v_mfma_f32_16x16x32_bf16 v[2:5], v[160:163], v[216:219], v[2:5]
	s_barrier
	s_setprio 0
	s_add_i32 s88, 0, 0x18000
	v_add_u32_e32 v1, s88, v210
	s_add_i32 s89, 0, 0x1c000
	ds_read_b128 v[132:135], v1
	ds_read_b128 v[136:139], v1 offset:1024
	ds_read_b128 v[140:143], v1 offset:2048
	ds_read_b128 v[144:147], v1 offset:3072
	v_add_u32_e32 v1, s89, v210
	ds_read_b128 v[148:151], v1
	ds_read_b128 v[152:155], v1 offset:1024
	ds_read_b128 v[156:159], v1 offset:2048
	ds_read_b128 v[160:163], v1 offset:3072
	s_add_u32 s64, s64, 0x2000
	s_addc_u32 s65, s65, 0
	s_mov_b32 m0, s57
	ds_read_b128 v[164:167], v211 offset:32768
	ds_read_b128 v[168:171], v211 offset:33792
	ds_read_b128 v[172:175], v211 offset:34816
	ds_read_b128 v[176:179], v211 offset:35840
	ds_read_b128 v[180:183], v211 offset:36864
	ds_read_b128 v[184:187], v211 offset:37888
	ds_read_b128 v[212:215], v211 offset:38912
	ds_read_b128 v[216:219], v211 offset:39936
	global_load_lds_dwordx4 v194, s[64:65]
	s_mov_b32 m0, s59
	s_nop 0
	global_load_lds_dwordx4 v190, s[64:65]
	s_waitcnt vmcnt(8)
	s_waitcnt lgkmcnt(0)
	s_setprio 1
	s_barrier
	v_mfma_f32_16x16x32_bf16 v[128:131], v[132:135], v[164:167], v[128:131]
	v_mfma_f32_16x16x32_bf16 v[124:127], v[140:143], v[164:167], v[124:127]
	v_mfma_f32_16x16x32_bf16 v[112:115], v[132:135], v[172:175], v[112:115]
	v_mfma_f32_16x16x32_bf16 v[108:111], v[140:143], v[172:175], v[108:111]
	v_mfma_f32_16x16x32_bf16 v[96:99], v[132:135], v[180:183], v[96:99]
	v_mfma_f32_16x16x32_bf16 v[92:95], v[140:143], v[180:183], v[92:95]
	v_mfma_f32_16x16x32_bf16 v[80:83], v[132:135], v[212:215], v[80:83]
	v_mfma_f32_16x16x32_bf16 v[76:79], v[140:143], v[212:215], v[76:79]
	v_mfma_f32_16x16x32_bf16 v[128:131], v[136:139], v[168:171], v[128:131]
	v_mfma_f32_16x16x32_bf16 v[124:127], v[144:147], v[168:171], v[124:127]
	v_mfma_f32_16x16x32_bf16 v[112:115], v[136:139], v[176:179], v[112:115]
	v_mfma_f32_16x16x32_bf16 v[108:111], v[144:147], v[176:179], v[108:111]
	v_mfma_f32_16x16x32_bf16 v[96:99], v[136:139], v[184:187], v[96:99]
	v_mfma_f32_16x16x32_bf16 v[92:95], v[144:147], v[184:187], v[92:95]
	v_mfma_f32_16x16x32_bf16 v[80:83], v[136:139], v[216:219], v[80:83]
	v_mfma_f32_16x16x32_bf16 v[76:79], v[144:147], v[216:219], v[76:79]
	v_mfma_f32_16x16x32_bf16 v[120:123], v[148:151], v[164:167], v[120:123]
	v_mfma_f32_16x16x32_bf16 v[116:119], v[156:159], v[164:167], v[116:119]
	v_mfma_f32_16x16x32_bf16 v[104:107], v[148:151], v[172:175], v[104:107]
	v_mfma_f32_16x16x32_bf16 v[100:103], v[156:159], v[172:175], v[100:103]
	v_mfma_f32_16x16x32_bf16 v[88:91], v[148:151], v[180:183], v[88:91]
	v_mfma_f32_16x16x32_bf16 v[84:87], v[156:159], v[180:183], v[84:87]
	v_mfma_f32_16x16x32_bf16 v[72:75], v[148:151], v[212:215], v[72:75]
	v_mfma_f32_16x16x32_bf16 v[68:71], v[156:159], v[212:215], v[68:71]
	v_mfma_f32_16x16x32_bf16 v[120:123], v[152:155], v[168:171], v[120:123]
	v_mfma_f32_16x16x32_bf16 v[116:119], v[160:163], v[168:171], v[116:119]
	v_mfma_f32_16x16x32_bf16 v[104:107], v[152:155], v[176:179], v[104:107]
	v_mfma_f32_16x16x32_bf16 v[100:103], v[160:163], v[176:179], v[100:103]
	v_mfma_f32_16x16x32_bf16 v[88:91], v[152:155], v[184:187], v[88:91]
	v_mfma_f32_16x16x32_bf16 v[84:87], v[160:163], v[184:187], v[84:87]
	v_mfma_f32_16x16x32_bf16 v[72:75], v[152:155], v[216:219], v[72:75]
	v_mfma_f32_16x16x32_bf16 v[68:71], v[160:163], v[216:219], v[68:71]
	s_barrier
	s_setprio 0
	s_add_u32 s98, s50, s10
	s_addc_u32 s99, s51, s11
	s_add_i32 s64, s88, s34
	s_mov_b32 m0, s64
	ds_read_b128 v[164:167], v211 offset:49152
	ds_read_b128 v[168:171], v211 offset:50176
	ds_read_b128 v[172:175], v211 offset:51200
	ds_read_b128 v[176:179], v211 offset:52224
	ds_read_b128 v[180:183], v211 offset:53248
	ds_read_b128 v[184:187], v211 offset:54272
	ds_read_b128 v[212:215], v211 offset:55296
	ds_read_b128 v[216:219], v211 offset:56320
	global_load_lds_dwordx4 v192, s[98:99]
	s_add_i32 m0, s64, 0x2000
	s_add_u32 s50, s50, 0x80080
	v_lshl_add_u64 v[6:7], v[222:223], 0, s[10:11]
	s_addc_u32 s51, s51, 0
	s_add_i32 s64, s89, s34
	global_load_lds_dwordx4 v[6:7], off
	s_mov_b32 m0, s64
	s_nop 0
	global_load_lds_dwordx4 v192, s[50:51]
	s_add_i32 m0, s64, 0x2000
	s_nop 0
	global_load_lds_dwordx4 v188, s[50:51]
	s_mov_b32 m0, s74
	s_nop 0
	global_load_lds_dwordx4 v194, s[48:49]
	s_mov_b32 m0, s75
	s_nop 0
	global_load_lds_dwordx4 v190, s[48:49]
	s_waitcnt vmcnt(8)
	s_waitcnt lgkmcnt(0)
	s_setprio 1
	s_barrier
	v_mfma_f32_16x16x32_bf16 v[64:67], v[132:135], v[164:167], v[64:67]
	v_mfma_f32_16x16x32_bf16 v[60:63], v[140:143], v[164:167], v[60:63]
	v_mfma_f32_16x16x32_bf16 v[48:51], v[132:135], v[172:175], v[48:51]
	v_mfma_f32_16x16x32_bf16 v[44:47], v[140:143], v[172:175], v[44:47]
	v_mfma_f32_16x16x32_bf16 v[32:35], v[132:135], v[180:183], v[32:35]
	v_mfma_f32_16x16x32_bf16 v[28:31], v[140:143], v[180:183], v[28:31]
	v_mfma_f32_16x16x32_bf16 v[16:19], v[132:135], v[212:215], v[16:19]
	v_mfma_f32_16x16x32_bf16 v[12:15], v[140:143], v[212:215], v[12:15]
	v_mfma_f32_16x16x32_bf16 v[64:67], v[136:139], v[168:171], v[64:67]
	v_mfma_f32_16x16x32_bf16 v[60:63], v[144:147], v[168:171], v[60:63]
	v_mfma_f32_16x16x32_bf16 v[48:51], v[136:139], v[176:179], v[48:51]
	v_mfma_f32_16x16x32_bf16 v[44:47], v[144:147], v[176:179], v[44:47]
	v_mfma_f32_16x16x32_bf16 v[32:35], v[136:139], v[184:187], v[32:35]
	v_mfma_f32_16x16x32_bf16 v[28:31], v[144:147], v[184:187], v[28:31]
	v_mfma_f32_16x16x32_bf16 v[16:19], v[136:139], v[216:219], v[16:19]
	v_mfma_f32_16x16x32_bf16 v[12:15], v[144:147], v[216:219], v[12:15]
	v_mfma_f32_16x16x32_bf16 v[56:59], v[148:151], v[164:167], v[56:59]
	v_mfma_f32_16x16x32_bf16 v[52:55], v[156:159], v[164:167], v[52:55]
	v_mfma_f32_16x16x32_bf16 v[40:43], v[148:151], v[172:175], v[40:43]
	v_mfma_f32_16x16x32_bf16 v[36:39], v[156:159], v[172:175], v[36:39]
	v_mfma_f32_16x16x32_bf16 v[24:27], v[148:151], v[180:183], v[24:27]
	v_mfma_f32_16x16x32_bf16 v[20:23], v[156:159], v[180:183], v[20:23]
	v_mfma_f32_16x16x32_bf16 v[6:9], v[148:151], v[212:215], v[8:11]
	v_mfma_f32_16x16x32_bf16 v[2:5], v[156:159], v[212:215], v[2:5]
	v_mfma_f32_16x16x32_bf16 v[56:59], v[152:155], v[168:171], v[56:59]
	v_mfma_f32_16x16x32_bf16 v[52:55], v[160:163], v[168:171], v[52:55]
	v_mfma_f32_16x16x32_bf16 v[40:43], v[152:155], v[176:179], v[40:43]
	v_mfma_f32_16x16x32_bf16 v[36:39], v[160:163], v[176:179], v[36:39]
	v_mfma_f32_16x16x32_bf16 v[24:27], v[152:155], v[184:187], v[24:27]
	v_mfma_f32_16x16x32_bf16 v[20:23], v[160:163], v[184:187], v[20:23]
	v_mfma_f32_16x16x32_bf16 v[8:11], v[152:155], v[216:219], v[6:9]
	v_mfma_f32_16x16x32_bf16 v[4:7], v[160:163], v[216:219], v[2:5]
	s_barrier
	s_setprio 0
	s_add_i32 s87, s87, 2
	s_add_u32 s41, s41, 0x100
	s_addc_u32 s86, s86, 0
	s_add_u32 s46, s46, 0x10000
	s_addc_u32 s47, s47, 0
	s_cmp_gt_u32 s87, 29
	s_cbranch_scc1 .LBB0_440

.LBB0_606:
	s_mov_b64 s[16:17], 0x80
	s_add_i32 m0, s44, 0x18000
	v_lshl_add_u64 v[2:3], v[2:3], 0, s[16:17]
	s_bfe_u32 s9, s96, 0x20006
	s_lshl_b32 s7, s1, 6
	global_load_lds_dwordx4 v[2:3], off
	s_add_i32 m0, s44, 0x1a000
	s_add_u32 s4, s12, 0x8000
	v_lshl_add_u64 v[0:1], v[0:1], 0, s[16:17]
	s_addc_u32 s5, s13, 0
	s_add_i32 s48, s44, 0x8000
	global_load_lds_dwordx4 v[0:1], off
	v_lshl_add_u64 v[0:1], s[4:5], 0, v[128:129]
	s_mov_b32 m0, s48
	s_add_i32 s49, s44, 0xa000
	global_load_lds_dwordx4 v[0:1], off
	v_lshl_add_u64 v[0:1], s[4:5], 0, v[132:133]
	s_add_u32 s4, s10, 0x100080
	s_mov_b32 m0, s49
	s_addc_u32 s5, s11, 0
	global_load_lds_dwordx4 v[0:1], off
	s_add_i32 m0, s44, 0x1c000
	v_lshl_add_u64 v[0:1], s[4:5], 0, v[130:131]
	global_load_lds_dwordx4 v[0:1], off
	v_lshl_add_u64 v[0:1], s[4:5], 0, v[134:135]
	s_add_i32 m0, s44, 0x1e000
	v_and_b32_e32 v148, 15, v228
	global_load_lds_dwordx4 v[0:1], off
	s_waitcnt vmcnt(8)
	s_barrier
	v_and_b32_e32 v0, 48, v228
	v_and_b32_e32 v1, 0xfffffc00, v5
	v_lshlrev_b32_e32 v3, 2, v228
	v_lshl_add_u32 v2, s1, 13, v1
	v_lshl_or_b32 v0, v148, 6, v0
	v_and_b32_e32 v3, 32, v3
	v_lshl_add_u32 v1, s9, 12, v1
	v_bitop3_b32 v5, v0, v2, v3 bitop3:0xde
	v_bitop3_b32 v149, v0, v1, v3 bitop3:0xde
	v_lshlrev_b32_e32 v0, 8, v4
	v_and_b32_e32 v0, 0x7ffffe00, v0
	v_lshlrev_b32_e32 v1, 5, v6
	v_add3_u32 v0, v7, v0, v1
	s_sext_i32_i8 s8, s0
	v_add_lshl_u32 v0, v0, v8, 1
	v_mov_b32_e32 v1, v131
	s_mov_b64 s[0:1], 0xa000
	v_lshl_add_u64 v[136:137], v[0:1], 0, s[0:1]
	v_lshlrev_b32_e32 v0, 8, v9
	v_and_b32_e32 v0, 0x7ffffe00, v0
	v_lshlrev_b32_e32 v1, 5, v10
	v_add3_u32 v0, v11, v0, v1
	s_waitcnt vmcnt(6)
	v_add_lshl_u32 v0, v0, v12, 1
	v_mov_b32_e32 v1, v131
	v_mov_b32_e32 v2, v131
	v_mov_b32_e32 v3, v131
	v_lshl_add_u64 v[138:139], v[0:1], 0, s[0:1]
	v_mov_b32_e32 v0, v131
	v_add_u32_e32 v150, 0, v5
	s_mov_b32 s50, 0
	v_mov_b64_e32 v[140:141], 0x100
	v_mov_b64_e32 v[142:143], 0xff
	s_add_i32 s51, 0, 0x10000
	s_add_i32 s56, 0, 0x14000
	s_mov_b64 s[18:19], 0x10000
	s_barrier
	s_branch .LBB0_608

.LBB0_614:
	s_ashr_i32 s23, s22, 31
	s_lshl_b64 s[26:27], s[22:23], 21
	s_add_u32 s26, s14, s26
	s_addc_u32 s27, s15, s27
	s_and_b64 s[28:29], s[4:5], exec
	s_cselect_b32 s23, s27, s13
	s_cselect_b32 s59, s26, s12
	s_ashr_i32 s21, s20, 31
	s_lshl_b64 s[28:29], s[20:21], 21
	s_add_u32 s28, s33, s28
	s_addc_u32 s29, s34, s29
	s_and_b64 s[36:37], s[4:5], exec
	s_cselect_b32 s21, s29, s11
	s_cselect_b32 s60, s28, s10
	s_add_u32 s61, s10, 0x100
	s_addc_u32 s62, s11, 0
	s_mov_b32 s63, -2
	s_mov_b64 s[36:37], 0x10000
	v_mov_b64_e32 v[144:145], v[138:139]
	v_mov_b64_e32 v[146:147], v[136:137]
	v_add_u32_e32 v151, s51, v149
	ds_read_b128 v[152:155], v151
	ds_read_b128 v[156:159], v151 offset:1024
	ds_read_b128 v[160:163], v151 offset:2048
	ds_read_b128 v[164:167], v151 offset:3072
	v_add_u32_e32 v151, s56, v149
	ds_read_b128 v[168:171], v151
	ds_read_b128 v[172:175], v151 offset:1024
	ds_read_b128 v[176:179], v151 offset:2048
	ds_read_b128 v[180:183], v151 offset:3072
	s_add_u32 s38, s12, s36
	s_addc_u32 s39, s13, s37
	s_cmp_eq_u32 s63, 60
	s_cselect_b32 s42, s59, s38
	s_cselect_b32 s43, s23, s39
	s_cselect_b32 s40, s60, s61
	s_cselect_b32 s41, s21, s62
	s_add_u32 s38, s42, 0x8000
	s_addc_u32 s39, s43, 0
	s_add_i32 m0, s44, 0xc000
	ds_read_b128 v[184:187], v150
	ds_read_b128 v[188:191], v150 offset:1024
	ds_read_b128 v[192:195], v150 offset:2048
	ds_read_b128 v[196:199], v150 offset:3072
	ds_read_b128 v[200:203], v150 offset:4096
	ds_read_b128 v[204:207], v150 offset:5120
	ds_read_b128 v[208:211], v150 offset:6144
	ds_read_b128 v[212:215], v150 offset:7168
	global_load_lds_dwordx4 v146, s[12:13]
	s_add_i32 m0, s44, 0xe000
	s_nop 0
	global_load_lds_dwordx4 v144, s[12:13]
	s_waitcnt vmcnt(8)
	s_waitcnt lgkmcnt(0)
	s_setprio 1
	s_barrier
	v_mfma_f32_16x16x32_bf16 v[124:127], v[152:155], v[184:187], 0
	v_mfma_f32_16x16x32_bf16 v[120:123], v[160:163], v[184:187], 0
	v_mfma_f32_16x16x32_bf16 v[108:111], v[152:155], v[192:195], 0
	v_mfma_f32_16x16x32_bf16 v[104:107], v[160:163], v[192:195], 0
	v_mfma_f32_16x16x32_bf16 v[92:95], v[152:155], v[200:203], 0
	v_mfma_f32_16x16x32_bf16 v[88:91], v[160:163], v[200:203], 0
	v_mfma_f32_16x16x32_bf16 v[76:79], v[152:155], v[208:211], 0
	v_mfma_f32_16x16x32_bf16 v[72:75], v[160:163], v[208:211], 0
	v_mfma_f32_16x16x32_bf16 v[124:127], v[156:159], v[188:191], v[124:127]
	v_mfma_f32_16x16x32_bf16 v[120:123], v[164:167], v[188:191], v[120:123]
	v_mfma_f32_16x16x32_bf16 v[108:111], v[156:159], v[196:199], v[108:111]
	v_mfma_f32_16x16x32_bf16 v[104:107], v[164:167], v[196:199], v[104:107]
	v_mfma_f32_16x16x32_bf16 v[92:95], v[156:159], v[204:207], v[92:95]
	v_mfma_f32_16x16x32_bf16 v[88:91], v[164:167], v[204:207], v[88:91]
	v_mfma_f32_16x16x32_bf16 v[76:79], v[156:159], v[212:215], v[76:79]
	v_mfma_f32_16x16x32_bf16 v[72:75], v[164:167], v[212:215], v[72:75]
	v_mfma_f32_16x16x32_bf16 v[116:119], v[168:171], v[184:187], 0
	v_mfma_f32_16x16x32_bf16 v[112:115], v[176:179], v[184:187], 0
	v_mfma_f32_16x16x32_bf16 v[100:103], v[168:171], v[192:195], 0
	v_mfma_f32_16x16x32_bf16 v[96:99], v[176:179], v[192:195], 0
	v_mfma_f32_16x16x32_bf16 v[84:87], v[168:171], v[200:203], 0
	v_mfma_f32_16x16x32_bf16 v[80:83], v[176:179], v[200:203], 0
	v_mfma_f32_16x16x32_bf16 v[68:71], v[168:171], v[208:211], 0
	v_mfma_f32_16x16x32_bf16 v[64:67], v[176:179], v[208:211], 0
	v_mfma_f32_16x16x32_bf16 v[116:119], v[172:175], v[188:191], v[116:119]
	v_mfma_f32_16x16x32_bf16 v[112:115], v[180:183], v[188:191], v[112:115]
	v_mfma_f32_16x16x32_bf16 v[100:103], v[172:175], v[196:199], v[100:103]
	v_mfma_f32_16x16x32_bf16 v[96:99], v[180:183], v[196:199], v[96:99]
	v_mfma_f32_16x16x32_bf16 v[84:87], v[172:175], v[204:207], v[84:87]
	v_mfma_f32_16x16x32_bf16 v[80:83], v[180:183], v[204:207], v[80:83]
	v_mfma_f32_16x16x32_bf16 v[68:71], v[172:175], v[212:215], v[68:71]
	v_mfma_f32_16x16x32_bf16 v[64:67], v[180:183], v[212:215], v[64:67]
	s_barrier
	s_setprio 0
	s_add_i32 s64, s51, s35
	s_mov_b32 m0, s64
	ds_read_b128 v[184:187], v150 offset:16384
	ds_read_b128 v[188:191], v150 offset:17408
	ds_read_b128 v[192:195], v150 offset:18432
	ds_read_b128 v[196:199], v150 offset:19456
	ds_read_b128 v[200:203], v150 offset:20480
	ds_read_b128 v[204:207], v150 offset:21504
	ds_read_b128 v[208:211], v150 offset:22528
	ds_read_b128 v[212:215], v150 offset:23552
	global_load_lds_dwordx4 v130, s[40:41]
	s_add_i32 m0, s64, 0x2000
	s_add_u32 s64, s40, 0x100000
	v_lshl_add_u64 v[218:219], s[40:41], 0, v[134:135]
	s_addc_u32 s65, s41, 0
	s_add_i32 s66, s56, s35
	global_load_lds_dwordx4 v[218:219], off
	s_mov_b32 m0, s66
	s_nop 0
	global_load_lds_dwordx4 v130, s[64:65]
	s_add_i32 m0, s66, 0x2000
	s_nop 0
	global_load_lds_dwordx4 v134, s[64:65]
	s_mov_b32 m0, s44
	s_nop 0
	global_load_lds_dwordx4 v128, s[42:43]
	s_mov_b32 m0, s45
	s_nop 0
	global_load_lds_dwordx4 v132, s[42:43]
	s_waitcnt vmcnt(8)
	s_waitcnt lgkmcnt(0)
	s_setprio 1
	s_barrier
	v_mfma_f32_16x16x32_bf16 v[60:63], v[152:155], v[184:187], 0
	v_mfma_f32_16x16x32_bf16 v[56:59], v[160:163], v[184:187], 0
	v_mfma_f32_16x16x32_bf16 v[44:47], v[152:155], v[192:195], 0
	v_mfma_f32_16x16x32_bf16 v[40:43], v[160:163], v[192:195], 0
	v_mfma_f32_16x16x32_bf16 v[28:31], v[152:155], v[200:203], 0
	v_mfma_f32_16x16x32_bf16 v[24:27], v[160:163], v[200:203], 0
	v_mfma_f32_16x16x32_bf16 v[12:15], v[152:155], v[208:211], 0
	v_mfma_f32_16x16x32_bf16 v[8:11], v[160:163], v[208:211], 0
	v_mfma_f32_16x16x32_bf16 v[60:63], v[156:159], v[188:191], v[60:63]
	v_mfma_f32_16x16x32_bf16 v[56:59], v[164:167], v[188:191], v[56:59]
	v_mfma_f32_16x16x32_bf16 v[44:47], v[156:159], v[196:199], v[44:47]
	v_mfma_f32_16x16x32_bf16 v[40:43], v[164:167], v[196:199], v[40:43]
	v_mfma_f32_16x16x32_bf16 v[28:31], v[156:159], v[204:207], v[28:31]
	v_mfma_f32_16x16x32_bf16 v[24:27], v[164:167], v[204:207], v[24:27]
	v_mfma_f32_16x16x32_bf16 v[12:15], v[156:159], v[212:215], v[12:15]
	v_mfma_f32_16x16x32_bf16 v[8:11], v[164:167], v[212:215], v[8:11]
	v_mfma_f32_16x16x32_bf16 v[52:55], v[168:171], v[184:187], 0
	v_mfma_f32_16x16x32_bf16 v[48:51], v[176:179], v[184:187], 0
	v_mfma_f32_16x16x32_bf16 v[36:39], v[168:171], v[192:195], 0
	v_mfma_f32_16x16x32_bf16 v[32:35], v[176:179], v[192:195], 0
	v_mfma_f32_16x16x32_bf16 v[20:23], v[168:171], v[200:203], 0
	v_mfma_f32_16x16x32_bf16 v[16:19], v[176:179], v[200:203], 0
	v_mfma_f32_16x16x32_bf16 v[4:7], v[168:171], v[208:211], 0
	v_mfma_f32_16x16x32_bf16 v[0:3], v[176:179], v[208:211], 0
	v_mfma_f32_16x16x32_bf16 v[52:55], v[172:175], v[188:191], v[52:55]
	v_mfma_f32_16x16x32_bf16 v[48:51], v[180:183], v[188:191], v[48:51]
	v_mfma_f32_16x16x32_bf16 v[36:39], v[172:175], v[196:199], v[36:39]
	v_mfma_f32_16x16x32_bf16 v[32:35], v[180:183], v[196:199], v[32:35]
	v_mfma_f32_16x16x32_bf16 v[20:23], v[172:175], v[204:207], v[20:23]
	v_mfma_f32_16x16x32_bf16 v[16:19], v[180:183], v[204:207], v[16:19]
	v_mfma_f32_16x16x32_bf16 v[4:7], v[172:175], v[212:215], v[4:7]
	v_mfma_f32_16x16x32_bf16 v[0:3], v[180:183], v[212:215], v[0:3]
	s_barrier
	s_setprio 0
	s_add_i32 s64, 0, 0x18000
	v_add_u32_e32 v151, s64, v149
	s_add_i32 s65, 0, 0x1c000
	ds_read_b128 v[152:155], v151
	ds_read_b128 v[156:159], v151 offset:1024
	ds_read_b128 v[160:163], v151 offset:2048
	ds_read_b128 v[164:167], v151 offset:3072
	v_add_u32_e32 v151, s65, v149
	ds_read_b128 v[168:171], v151
	ds_read_b128 v[172:175], v151 offset:1024
	ds_read_b128 v[176:179], v151 offset:2048
	ds_read_b128 v[180:183], v151 offset:3072
	s_add_u32 s42, s42, 0x2000
	s_addc_u32 s43, s43, 0
	s_mov_b32 m0, s46
	ds_read_b128 v[184:187], v150 offset:32768
	ds_read_b128 v[188:191], v150 offset:33792
	ds_read_b128 v[192:195], v150 offset:34816
	ds_read_b128 v[196:199], v150 offset:35840
	ds_read_b128 v[200:203], v150 offset:36864
	ds_read_b128 v[204:207], v150 offset:37888
	ds_read_b128 v[208:211], v150 offset:38912
	ds_read_b128 v[212:215], v150 offset:39936
	global_load_lds_dwordx4 v128, s[42:43]
	s_mov_b32 m0, s47
	s_nop 0
	global_load_lds_dwordx4 v132, s[42:43]
	s_waitcnt vmcnt(8)
	s_waitcnt lgkmcnt(0)
	s_setprio 1
	s_barrier
	v_mfma_f32_16x16x32_bf16 v[124:127], v[152:155], v[184:187], v[124:127]
	v_mfma_f32_16x16x32_bf16 v[120:123], v[160:163], v[184:187], v[120:123]
	v_mfma_f32_16x16x32_bf16 v[108:111], v[152:155], v[192:195], v[108:111]
	v_mfma_f32_16x16x32_bf16 v[104:107], v[160:163], v[192:195], v[104:107]
	v_mfma_f32_16x16x32_bf16 v[92:95], v[152:155], v[200:203], v[92:95]
	v_mfma_f32_16x16x32_bf16 v[88:91], v[160:163], v[200:203], v[88:91]
	v_mfma_f32_16x16x32_bf16 v[76:79], v[152:155], v[208:211], v[76:79]
	v_mfma_f32_16x16x32_bf16 v[72:75], v[160:163], v[208:211], v[72:75]
	v_mfma_f32_16x16x32_bf16 v[124:127], v[156:159], v[188:191], v[124:127]
	v_mfma_f32_16x16x32_bf16 v[120:123], v[164:167], v[188:191], v[120:123]
	v_mfma_f32_16x16x32_bf16 v[108:111], v[156:159], v[196:199], v[108:111]
	v_mfma_f32_16x16x32_bf16 v[104:107], v[164:167], v[196:199], v[104:107]
	v_mfma_f32_16x16x32_bf16 v[92:95], v[156:159], v[204:207], v[92:95]
	v_mfma_f32_16x16x32_bf16 v[88:91], v[164:167], v[204:207], v[88:91]
	v_mfma_f32_16x16x32_bf16 v[76:79], v[156:159], v[212:215], v[76:79]
	v_mfma_f32_16x16x32_bf16 v[72:75], v[164:167], v[212:215], v[72:75]
	v_mfma_f32_16x16x32_bf16 v[116:119], v[168:171], v[184:187], v[116:119]
	v_mfma_f32_16x16x32_bf16 v[112:115], v[176:179], v[184:187], v[112:115]
	v_mfma_f32_16x16x32_bf16 v[100:103], v[168:171], v[192:195], v[100:103]
	v_mfma_f32_16x16x32_bf16 v[96:99], v[176:179], v[192:195], v[96:99]
	v_mfma_f32_16x16x32_bf16 v[84:87], v[168:171], v[200:203], v[84:87]
	v_mfma_f32_16x16x32_bf16 v[80:83], v[176:179], v[200:203], v[80:83]
	v_mfma_f32_16x16x32_bf16 v[68:71], v[168:171], v[208:211], v[68:71]
	v_mfma_f32_16x16x32_bf16 v[64:67], v[176:179], v[208:211], v[64:67]
	v_mfma_f32_16x16x32_bf16 v[116:119], v[172:175], v[188:191], v[116:119]
	v_mfma_f32_16x16x32_bf16 v[112:115], v[180:183], v[188:191], v[112:115]
	v_mfma_f32_16x16x32_bf16 v[100:103], v[172:175], v[196:199], v[100:103]
	v_mfma_f32_16x16x32_bf16 v[96:99], v[180:183], v[196:199], v[96:99]
	v_mfma_f32_16x16x32_bf16 v[84:87], v[172:175], v[204:207], v[84:87]
	v_mfma_f32_16x16x32_bf16 v[80:83], v[180:183], v[204:207], v[80:83]
	v_mfma_f32_16x16x32_bf16 v[68:71], v[172:175], v[212:215], v[68:71]
	v_mfma_f32_16x16x32_bf16 v[64:67], v[180:183], v[212:215], v[64:67]
	s_barrier
	s_setprio 0
	s_add_u32 s98, s40, s16
	s_addc_u32 s99, s41, s17
	s_add_i32 s42, s64, s35
	s_mov_b32 m0, s42
	ds_read_b128 v[184:187], v150 offset:49152
	ds_read_b128 v[188:191], v150 offset:50176
	ds_read_b128 v[192:195], v150 offset:51200
	ds_read_b128 v[196:199], v150 offset:52224
	ds_read_b128 v[200:203], v150 offset:53248
	ds_read_b128 v[204:207], v150 offset:54272
	ds_read_b128 v[208:211], v150 offset:55296
	ds_read_b128 v[212:215], v150 offset:56320
	global_load_lds_dwordx4 v130, s[98:99]
	s_add_i32 m0, s42, 0x2000
	s_add_u32 s40, s40, 0x100080
	v_lshl_add_u64 v[216:217], v[218:219], 0, s[16:17]
	s_addc_u32 s41, s41, 0
	s_add_i32 s42, s65, s35
	global_load_lds_dwordx4 v[216:217], off
	s_mov_b32 m0, s42
	s_nop 0
	global_load_lds_dwordx4 v130, s[40:41]
	s_add_i32 m0, s42, 0x2000
	s_nop 0
	global_load_lds_dwordx4 v134, s[40:41]
	s_mov_b32 m0, s48
	s_nop 0
	global_load_lds_dwordx4 v128, s[38:39]
	s_mov_b32 m0, s49
	s_nop 0
	global_load_lds_dwordx4 v132, s[38:39]
	s_waitcnt vmcnt(8)
	s_waitcnt lgkmcnt(0)
	s_setprio 1
	s_barrier
	v_mfma_f32_16x16x32_bf16 v[60:63], v[152:155], v[184:187], v[60:63]
	v_mfma_f32_16x16x32_bf16 v[56:59], v[160:163], v[184:187], v[56:59]
	v_mfma_f32_16x16x32_bf16 v[44:47], v[152:155], v[192:195], v[44:47]
	v_mfma_f32_16x16x32_bf16 v[40:43], v[160:163], v[192:195], v[40:43]
	v_mfma_f32_16x16x32_bf16 v[28:31], v[152:155], v[200:203], v[28:31]
	v_mfma_f32_16x16x32_bf16 v[24:27], v[160:163], v[200:203], v[24:27]
	v_mfma_f32_16x16x32_bf16 v[12:15], v[152:155], v[208:211], v[12:15]
	v_mfma_f32_16x16x32_bf16 v[8:11], v[160:163], v[208:211], v[8:11]
	v_mfma_f32_16x16x32_bf16 v[60:63], v[156:159], v[188:191], v[60:63]
	v_mfma_f32_16x16x32_bf16 v[56:59], v[164:167], v[188:191], v[56:59]
	v_mfma_f32_16x16x32_bf16 v[44:47], v[156:159], v[196:199], v[44:47]
	v_mfma_f32_16x16x32_bf16 v[40:43], v[164:167], v[196:199], v[40:43]
	v_mfma_f32_16x16x32_bf16 v[28:31], v[156:159], v[204:207], v[28:31]
	v_mfma_f32_16x16x32_bf16 v[24:27], v[164:167], v[204:207], v[24:27]
	v_mfma_f32_16x16x32_bf16 v[12:15], v[156:159], v[212:215], v[12:15]
	v_mfma_f32_16x16x32_bf16 v[8:11], v[164:167], v[212:215], v[8:11]
	v_mfma_f32_16x16x32_bf16 v[52:55], v[168:171], v[184:187], v[52:55]
	v_mfma_f32_16x16x32_bf16 v[48:51], v[176:179], v[184:187], v[48:51]
	v_mfma_f32_16x16x32_bf16 v[36:39], v[168:171], v[192:195], v[36:39]
	v_mfma_f32_16x16x32_bf16 v[32:35], v[176:179], v[192:195], v[32:35]
	v_mfma_f32_16x16x32_bf16 v[20:23], v[168:171], v[200:203], v[20:23]
	v_mfma_f32_16x16x32_bf16 v[16:19], v[176:179], v[200:203], v[16:19]
	v_mfma_f32_16x16x32_bf16 v[4:7], v[168:171], v[208:211], v[4:7]
	v_mfma_f32_16x16x32_bf16 v[0:3], v[176:179], v[208:211], v[0:3]
	v_mfma_f32_16x16x32_bf16 v[52:55], v[172:175], v[188:191], v[52:55]
	v_mfma_f32_16x16x32_bf16 v[48:51], v[180:183], v[188:191], v[48:51]
	v_mfma_f32_16x16x32_bf16 v[36:39], v[172:175], v[196:199], v[36:39]
	v_mfma_f32_16x16x32_bf16 v[32:35], v[180:183], v[196:199], v[32:35]
	v_mfma_f32_16x16x32_bf16 v[20:23], v[172:175], v[204:207], v[20:23]
	v_mfma_f32_16x16x32_bf16 v[16:19], v[180:183], v[204:207], v[16:19]
	v_mfma_f32_16x16x32_bf16 v[4:7], v[172:175], v[212:215], v[4:7]
	v_mfma_f32_16x16x32_bf16 v[0:3], v[180:183], v[212:215], v[0:3]
	s_barrier
	s_setprio 0
	s_add_i32 s63, s63, 2
	s_add_u32 s61, s61, 0x100
	s_addc_u32 s62, s62, 0
	s_add_u32 s36, s36, 0x10000
	s_addc_u32 s37, s37, 0
	v_lshl_add_u64 v[146:147], v[146:147], 0, s[18:19]
	s_cmp_gt_u32 s63, 61
	v_lshl_add_u64 v[144:145], v[144:145], 0, s[18:19]
